# combo7 + attention (wave-level pipelining of softmax/P.V, K-fragment reads hoisted, set-up parameter loads issued up front) + next-row prefetch in the f32-source modulate loop and the final RMSNorm lo
# speedup vs baseline: 1.0108x; 1.0000x over previous
; template <int MODE, bool SRC32>
; __device__ __forceinline__ void phase_mod(const float* x32, _Float16* xh, float* out32, bf16* h, const float* gprev, const float* gain, const float* shiftv, const float* scalev, int wave, int lane) {
;     const int blk = (int)blockIdx.x, b = blk >> 5, r0 = blk * 128 + wave * 16;
;     f32x4 A[8], Sh[8], G3[8];
; #pragma unroll
;     for (int k = 0; k < 8; ++k) {
;         const int d = 512 * (k >> 1) + 8 * lane + 4 * (k & 1);
;         if (MODE != 2) { const f32x4 g = *(const f32x4*)(gain + d), sc = *(const f32x4*)(scalev + (size_t)b * NMOD + d); A[k] = g * (sc + 1.0f); Sh[k] = *(const f32x4*)(shiftv + (size_t)b * NMOD + d); }
;         if (MODE != 0) G3[k] = *(const f32x4*)(gprev + d);
;     }
;     for (int i = 0; i < 16; ++i) {
;         const size_t ro = (size_t)(r0 + i) * D + 8 * lane;
;         f32x4 v[8]; float ss = 0.f;
; #pragma unroll
;         for (int j = 0; j < 4; ++j) {
;             if (SRC32) { v[2 * j] = *(const f32x4*)(x32 + ro + 512 * j); v[2 * j + 1] = *(const f32x4*)(x32 + ro + 512 * j + 4); }
;             else h8_to_f(*(const h16x8*)(xh + ro + 512 * j), v[2 * j], v[2 * j + 1]);
;         }
.LBB0_103:
	s_and_b64 vcc, exec, s[0:1]
	s_cbranch_vccz .LBB0_106
	v_mov_b32_e32 v75, v169
	v_lshlrev_b64 v[60:61], 2, v[74:75]
	v_mov_b32_e32 v73, v169
	v_lshl_add_u64 v[36:37], s[8:9], 0, v[60:61]
	v_lshl_add_u64 v[44:45], s[20:21], 0, v[60:61]
	v_lshlrev_b64 v[62:63], 2, v[72:73]
	global_load_dwordx4 v[4:7], v[78:79], off offset:16
	global_load_dwordx4 v[8:11], v[76:77], off offset:16
	global_load_dwordx4 v[12:15], v[78:79], off offset:2048
	global_load_dwordx4 v[16:19], v[78:79], off offset:2064
	global_load_dwordx4 v[20:23], v[76:77], off offset:2048
	global_load_dwordx4 v[24:27], v[76:77], off offset:2064
	global_load_dwordx4 v[28:31], v[36:37], off
	global_load_dwordx4 v[32:35], v[44:45], off
	s_nop 0
	global_load_dwordx4 v[36:39], v[36:37], off offset:16
	v_lshl_add_u64 v[52:53], s[8:9], 0, v[62:63]
	global_load_dwordx4 v[40:43], v[52:53], off
	s_nop 0
	global_load_dwordx4 v[44:47], v[44:45], off offset:16
	v_lshl_add_u64 v[56:57], s[20:21], 0, v[62:63]
	global_load_dwordx4 v[48:51], v[56:57], off
	s_nop 0
	global_load_dwordx4 v[52:55], v[52:53], off offset:16
	v_readlane_b32 s0, v253, 7
	v_cmp_lt_i32_e32 vcc, v222, v216
	s_add_i32 s0, s12, s0
	s_ashr_i32 s1, s0, 31
	v_readlane_b32 s8, v252, 19
	v_readlane_b32 s9, v252, 20
	v_mov_b32_e32 v69, v169
	v_readlane_b32 s20, v252, 31
	v_readlane_b32 s21, v252, 32
	v_readlane_b32 s20, v255, 2
	v_readlane_b32 s21, v255, 3
	v_readlane_b32 s10, v252, 21
	v_readlane_b32 s11, v252, 22
	v_readlane_b32 s12, v252, 23
	v_readlane_b32 s13, v252, 24
	v_readlane_b32 s14, v252, 25
	v_readlane_b32 s15, v252, 26
	v_readlane_b32 s16, v252, 27
	v_readlane_b32 s17, v252, 28
	v_readlane_b32 s18, v252, 29
	v_readlane_b32 s19, v252, 30
	v_readlane_b32 s22, v252, 33
	v_readlane_b32 s23, v252, 34
	s_waitcnt vmcnt(12)
	v_pk_add_f32 v[58:59], v[6:7], 1.0 op_sel_hi:[1,0]
	s_waitcnt vmcnt(11)
	v_pk_mul_f32 v[72:73], v[10:11], v[58:59]
	global_load_dwordx4 v[56:59], v[56:57], off offset:16
	v_pk_add_f32 v[74:75], v[4:5], 1.0 op_sel_hi:[1,0]
	s_waitcnt vmcnt(11)
	v_pk_add_f32 v[10:11], v[12:13], 1.0 op_sel_hi:[1,0]
	v_pk_mul_f32 v[74:75], v[8:9], v[74:75]
	v_pk_add_f32 v[8:9], v[14:15], 1.0 op_sel_hi:[1,0]
	s_waitcnt vmcnt(10)
	v_pk_add_f32 v[18:19], v[18:19], 1.0 op_sel_hi:[1,0]
	v_pk_add_f32 v[16:17], v[16:17], 1.0 op_sel_hi:[1,0]
	global_load_dwordx4 v[4:7], v[70:71], off offset:16
	s_waitcnt vmcnt(10)
	v_pk_mul_f32 v[76:77], v[22:23], v[8:9]
	v_pk_mul_f32 v[78:79], v[20:21], v[10:11]
	global_load_dwordx4 v[8:11], v[70:71], off offset:2064
	global_load_dwordx4 v[12:15], v[70:71], off offset:2048
	v_lshl_add_u64 v[20:21], s[6:7], 0, v[60:61]
	v_lshl_add_u64 v[60:61], s[6:7], 0, v[62:63]
	s_waitcnt vmcnt(11)
	v_pk_mul_f32 v[70:71], v[26:27], v[18:19]
	v_pk_mul_f32 v[80:81], v[24:25], v[16:17]
	s_waitcnt vmcnt(10)
	v_pk_add_f32 v[16:17], v[30:31], 1.0 op_sel_hi:[1,0]
	v_pk_add_f32 v[18:19], v[28:29], 1.0 op_sel_hi:[1,0]
	s_waitcnt vmcnt(8)
	v_pk_add_f32 v[24:25], v[38:39], 1.0 op_sel_hi:[1,0]
	v_pk_add_f32 v[26:27], v[36:37], 1.0 op_sel_hi:[1,0]
	v_pk_mul_f32 v[82:83], v[34:35], v[16:17]
	v_pk_mul_f32 v[84:85], v[32:33], v[18:19]
	global_load_dwordx4 v[16:19], v[20:21], off offset:16
	s_nop 0
	global_load_dwordx4 v[20:23], v[20:21], off
	s_waitcnt vmcnt(8)
	v_pk_mul_f32 v[86:87], v[46:47], v[24:25]
	v_pk_mul_f32 v[88:89], v[44:45], v[26:27]
	global_load_dwordx4 v[24:27], v[60:61], off offset:16
	global_load_dwordx4 v[28:31], v[60:61], off
	v_cndmask_b32_e32 v36, v215, v222, vcc
	v_cmp_lt_i32_e32 vcc, v221, v216
	v_pk_add_f32 v[32:33], v[42:43], 1.0 op_sel_hi:[1,0]
	s_lshl_b64 s[6:7], s[0:1], 13
	v_cndmask_b32_e32 v37, v215, v221, vcc
	v_cmp_lt_i32_e32 vcc, v220, v216
	s_waitcnt vmcnt(9)
	v_pk_mul_f32 v[90:91], v[50:51], v[32:33]
	s_waitcnt vmcnt(8)
	v_pk_add_f32 v[32:33], v[54:55], 1.0 op_sel_hi:[1,0]
	v_cndmask_b32_e32 v38, v215, v220, vcc
	v_cmp_lt_i32_e32 vcc, v219, v216
	s_add_u32 s6, s8, s6
	s_addc_u32 s7, s9, s7
	v_cndmask_b32_e32 v39, v215, v219, vcc
	v_cmp_lt_i32_e32 vcc, v218, v216
	s_lshl_b64 s[0:1], s[0:1], 12
	v_pk_add_f32 v[34:35], v[40:41], 1.0 op_sel_hi:[1,0]
	s_add_u32 s0, s58, s0
	v_pk_mul_f32 v[92:93], v[48:49], v[34:35]
	v_pk_add_f32 v[34:35], v[52:53], 1.0 op_sel_hi:[1,0]
	s_addc_u32 s1, s59, s1
	v_lshlrev_b32_e32 v100, 2, v36
	v_lshlrev_b32_e32 v101, 2, v37
	v_lshlrev_b32_e32 v102, 2, v38
	v_lshlrev_b32_e32 v103, 2, v39
	s_waitcnt vmcnt(7)
	v_pk_mul_f32 v[94:95], v[58:59], v[32:33]
	v_cndmask_b32_e32 v32, v215, v218, vcc
	v_cmp_lt_i32_e32 vcc, v217, v216
	v_lshlrev_b32_e32 v104, 2, v32
	v_pk_mul_f32 v[96:97], v[56:57], v[34:35]
	v_cndmask_b32_e32 v33, v215, v217, vcc
	v_lshlrev_b32_e32 v105, 2, v33
	v_lshlrev_b64 v[32:33], 5, v[68:69]
	v_lshl_add_u64 v[98:99], s[6:7], 0, v[32:33]
	v_lshl_add_u64 v[68:69], v[68:69], 4, s[0:1]
	s_mov_b64 s[0:1], 0x1000
	s_mov_b64 s[6:7], 0
	v_lshl_add_u64 v[156:157], v[98:99], 0, s[0:1]
	v_mov_b32_e32 v158, 0x2000
	v_mov_b32_e32 v159, 0
	global_load_dwordx4 v[136:139], v[156:157], off offset:-4096
	global_load_dwordx4 v[132:135], v[156:157], off offset:-4080
	global_load_dwordx4 v[128:131], v[156:157], off offset:-2048
	global_load_dwordx4 v[124:127], v[156:157], off offset:-2032
	global_load_dwordx4 v[144:147], v[156:157], off
	global_load_dwordx4 v[140:143], v[156:157], off offset:16
	global_load_dwordx4 v[148:151], v[156:157], off offset:2064
	global_load_dwordx4 v[152:155], v[156:157], off offset:2048
	s_waitcnt vmcnt(0)
; template <int MODE, bool SRC32>
; __device__ __forceinline__ void phase_mod(const float* x32, _Float16* xh, float* out32, bf16* h, const float* gprev, const float* gain, const float* shiftv, const float* scalev, int wave, int lane) {
;     ...
;     for (int i = 0; i < 16; ++i) {
;         const size_t ro = (size_t)(r0 + i) * D + 8 * lane;
;         f32x4 v[8]; float ss = 0.f;
; #pragma unroll
;         for (int j = 0; j < 4; ++j) {
;             if (SRC32) { v[2 * j] = *(const f32x4*)(x32 + ro + 512 * j); v[2 * j + 1] = *(const f32x4*)(x32 + ro + 512 * j + 4); }
;             else h8_to_f(*(const h16x8*)(xh + ro + 512 * j), v[2 * j], v[2 * j + 1]);
;         }
.LBB0_105:
	s_waitcnt vmcnt(4)
	v_mov_b64_e32 v[32:33], v[124:125]
	v_mov_b64_e32 v[34:35], v[126:127]
	v_mov_b64_e32 v[36:37], v[128:129]
	v_mov_b64_e32 v[38:39], v[130:131]
	v_mov_b64_e32 v[40:41], v[132:133]
	v_mov_b64_e32 v[42:43], v[134:135]
	v_mov_b64_e32 v[44:45], v[136:137]
	v_mov_b64_e32 v[46:47], v[138:139]
	v_mov_b64_e32 v[48:49], v[140:141]
	v_mov_b64_e32 v[50:51], v[142:143]
	v_mov_b64_e32 v[52:53], v[144:145]
	v_mov_b64_e32 v[54:55], v[146:147]
	v_mov_b64_e32 v[56:57], v[148:149]
	v_mov_b64_e32 v[58:59], v[150:151]
	v_mov_b64_e32 v[60:61], v[152:153]
	v_mov_b64_e32 v[62:63], v[154:155]
	s_add_u32 s6, s6, 0x2000
	s_addc_u32 s7, s7, 0
	s_cmp_eq_u32 s6, 0x20000
	s_cbranch_scc1 .Lmodpf32_skip
	v_lshl_add_u64 v[156:157], v[156:157], 0, v[158:159]
	global_load_dwordx4 v[136:139], v[156:157], off offset:-4096
	global_load_dwordx4 v[132:135], v[156:157], off offset:-4080
	global_load_dwordx4 v[128:131], v[156:157], off offset:-2048
	global_load_dwordx4 v[124:127], v[156:157], off offset:-2032
	global_load_dwordx4 v[144:147], v[156:157], off
	global_load_dwordx4 v[140:143], v[156:157], off offset:16
	global_load_dwordx4 v[148:151], v[156:157], off offset:2064
	global_load_dwordx4 v[152:155], v[156:157], off offset:2048
; __device__ __forceinline__ unsigned cvt_pk_bf16(float lo, float hi) { unsigned r; asm volatile("v_cvt_pk_bf16_f32 %0, %1, %2" : "=v"(r) : "v"(lo), "v"(hi)); return r; }
; __device__ __forceinline__ h16x8 f_to_h8(const f32x4 a, const f32x4 b) { return (h16x8){(_Float16)a[0], (_Float16)a[1], (_Float16)a[2], (_Float16)a[3], (_Float16)b[0], (_Float16)b[1], (_Float16)b[2], (_Float16)b[3]}; }
; template <int MODE, bool SRC32>
; __device__ __forceinline__ void phase_mod(const float* x32, _Float16* xh, float* out32, bf16* h, const float* gprev, const float* gain, const float* shiftv, const float* scalev, int wave, int lane) {
;     ...
; #pragma unroll
;         for (int k = 0; k < 8; ++k) ss += (v[k][0] * v[k][0] + v[k][1] * v[k][1]) + (v[k][2] * v[k][2] + v[k][3] * v[k][3]);
;         ss = wave_sum(ss);
;         float rstd = 1.0f / sqrtf(ss * (1.0f / D) + EPS);
;         if (MODE != 0) {
;             float s2 = 0.f;
; #pragma unroll
;             for (int k = 0; k < 8; ++k) { v[k] = v[k] * rstd * G3[k]; s2 += (v[k][0] * v[k][0] + v[k][1] * v[k][1]) + (v[k][2] * v[k][2] + v[k][3] * v[k][3]); }
; #pragma unroll
;             for (int j = 0; j < 4; ++j) {
;                 if (MODE == 1) *(h16x8*)(xh + ro + 512 * j) = f_to_h8(v[2 * j], v[2 * j + 1]);
;                 else { *(f32x4*)(out32 + ro + 512 * j) = v[2 * j]; *(f32x4*)(out32 + ro + 512 * j + 4) = v[2 * j + 1]; }
;             }
;             if (MODE == 2) continue;
;             s2 = wave_sum(s2);
;             rstd = 1.0f / sqrtf(s2 * (1.0f / D) + EPS);
;         }
; #pragma unroll
;         for (int j = 0; j < 4; ++j) { const f32x4 o0 = v[2 * j] * rstd * A[2 * j] + Sh[2 * j], o1 = v[2 * j + 1] * rstd * A[2 * j + 1] + Sh[2 * j + 1];
;             u32x4 w; w.x = cvt_pk_bf16(o0[0], o0[1]); w.y = cvt_pk_bf16(o0[2], o0[3]); w.z = cvt_pk_bf16(o1[0], o1[1]); w.w = cvt_pk_bf16(o1[2], o1[3]);
;             *(u32x4*)(h + ro + 512 * j) = w; }
.Lmodpf32_skip:
	v_mov_b32_e32 v108, v45
	v_mov_b32_e32 v109, v41
	v_mov_b32_e32 v112, v47
	v_mov_b32_e32 v113, v43
	v_mov_b32_e32 v106, v44
	v_mov_b32_e32 v107, v40
	v_mov_b32_e32 v110, v46
	v_mov_b32_e32 v111, v42
	v_pk_mul_f32 v[114:115], v[38:39], v[38:39]
	v_pk_mul_f32 v[116:117], v[36:37], v[36:37]
	v_pk_mul_f32 v[108:109], v[108:109], v[108:109]
	v_pk_mul_f32 v[112:113], v[112:113], v[112:113]
	v_pk_mov_b32 v[120:121], v[116:117], v[114:115] op_sel:[1,0]
	v_mov_b32_e32 v117, v115
	v_pk_fma_f32 v[106:107], v[106:107], v[106:107], v[108:109]
	v_pk_fma_f32 v[108:109], v[110:111], v[110:111], v[112:113]
	v_mul_f32_e32 v118, v33, v33
	v_mul_f32_e32 v114, v35, v35
	v_pk_add_f32 v[110:111], v[120:121], v[116:117]
	v_pk_add_f32 v[106:107], v[106:107], v[108:109]
	v_pk_fma_f32 v[118:119], v[32:33], v[32:33], v[118:119] op_sel_hi:[1,1,0]
	v_pk_fma_f32 v[114:115], v[34:35], v[34:35], v[114:115] op_sel_hi:[1,1,0]
	v_mul_f32_e32 v120, v52, v52
	v_mul_f32_e32 v121, v53, v53
	v_pk_add_f32 v[110:111], v[110:111], v[110:111] op_sel:[0,1] op_sel_hi:[1,0]
	v_pk_add_f32 v[106:107], v[106:107], v[106:107] op_sel:[0,1] op_sel_hi:[1,0]
	v_pk_mul_f32 v[112:113], v[50:51], v[50:51]
	v_pk_mul_f32 v[116:117], v[48:49], v[48:49]
	v_mul_f32_e32 v119, v54, v54
	v_mul_f32_e32 v115, v55, v55
	v_mov_b32_e32 v111, v121
	v_mov_b32_e32 v107, v120
	v_pk_mov_b32 v[108:109], v[116:117], v[112:113] op_sel:[1,0]
	v_mov_b32_e32 v117, v113
	v_pk_add_f32 v[112:113], v[118:119], v[114:115]
	v_pk_add_f32 v[106:107], v[106:107], v[110:111]
	v_pk_add_f32 v[108:109], v[108:109], v[116:117]
	v_mul_f32_e32 v114, v61, v61
	v_mul_f32_e32 v116, v63, v63
	v_pk_add_f32 v[106:107], v[106:107], v[112:113]
	v_mul_f32_e32 v122, v56, v56
	v_mul_f32_e32 v123, v57, v57
	v_mul_f32_e32 v118, v58, v58
	v_mul_f32_e32 v119, v59, v59
	v_pk_fma_f32 v[114:115], v[60:61], v[60:61], v[114:115] op_sel_hi:[1,1,0]
	v_pk_fma_f32 v[116:117], v[62:63], v[62:63], v[116:117] op_sel_hi:[1,1,0]
	v_pk_add_f32 v[108:109], v[108:109], v[108:109] op_sel:[0,1] op_sel_hi:[1,0]
	v_pk_add_f32 v[106:107], v[106:107], v[106:107] op_sel:[0,1] op_sel_hi:[1,0]
	v_mov_b32_e32 v115, v118
	v_mov_b32_e32 v117, v119
	v_mov_b32_e32 v109, v123
	v_mov_b32_e32 v107, v122
	v_pk_add_f32 v[114:115], v[114:115], v[116:117]
	v_pk_add_f32 v[106:107], v[106:107], v[108:109]
	s_nop 0
	v_pk_add_f32 v[106:107], v[106:107], v[114:115]
	s_nop 0
	v_add_f32_e32 v106, v106, v107
	ds_bpermute_b32 v107, v100, v106
	s_waitcnt lgkmcnt(0)
	v_add_f32_e32 v106, v106, v107
	ds_bpermute_b32 v107, v101, v106
	s_waitcnt lgkmcnt(0)
	v_add_f32_e32 v106, v106, v107
	ds_bpermute_b32 v107, v102, v106
	s_waitcnt lgkmcnt(0)
	v_add_f32_e32 v106, v106, v107
	ds_bpermute_b32 v107, v103, v106
	s_waitcnt lgkmcnt(0)
	v_add_f32_e32 v106, v106, v107
	ds_bpermute_b32 v107, v104, v106
	s_waitcnt lgkmcnt(0)
	v_add_f32_e32 v106, v106, v107
	ds_bpermute_b32 v107, v105, v106
	s_waitcnt lgkmcnt(0)
	v_add_f32_e32 v106, v106, v107
	v_fmamk_f32 v106, v106, 0x3a000000, v223
	v_mul_f32_e32 v107, 0x4f800000, v106
	v_cmp_gt_f32_e32 vcc, s62, v106
	s_nop 1
	v_cndmask_b32_e32 v106, v106, v107, vcc
	v_sqrt_f32_e32 v107, v106
	s_nop 0
	v_add_u32_e32 v108, -1, v107
	v_add_u32_e32 v109, 1, v107
	v_fma_f32 v110, -v108, v107, v106
	v_fma_f32 v111, -v109, v107, v106
	v_cmp_ge_f32_e64 s[36:37], 0, v110
	s_nop 1
	v_cndmask_b32_e64 v107, v107, v108, s[36:37]
	v_cmp_lt_f32_e64 s[36:37], 0, v111
	s_nop 1
	v_cndmask_b32_e64 v107, v107, v109, s[36:37]
	v_mul_f32_e32 v108, 0x37800000, v107
	v_cndmask_b32_e32 v107, v107, v108, vcc
	v_cmp_class_f32_e32 vcc, v106, v224
	s_nop 1
	v_cndmask_b32_e32 v106, v107, v106, vcc
	v_div_scale_f32 v107, s[0:1], v106, v106, 1.0
	v_rcp_f32_e32 v109, v107
	v_div_scale_f32 v108, vcc, 1.0, v106, 1.0
	s_mov_b64 s[0:1], 0x1000
	v_fma_f32 v110, -v107, v109, 1.0
	v_fmac_f32_e32 v109, v110, v109
	v_mul_f32_e32 v110, v108, v109
	v_fma_f32 v111, -v107, v110, v108
	v_fmac_f32_e32 v110, v111, v109
	v_fma_f32 v107, -v107, v110, v108
	v_div_fmas_f32 v107, v107, v109, v110
	v_div_fixup_f32 v106, v107, v106, 1.0
	v_pk_mul_f32 v[44:45], v[44:45], v[106:107] op_sel_hi:[1,0]
	v_pk_mul_f32 v[46:47], v[46:47], v[106:107] op_sel_hi:[1,0]
	v_pk_mul_f32 v[40:41], v[40:41], v[106:107] op_sel_hi:[1,0]
	v_pk_mul_f32 v[42:43], v[42:43], v[106:107] op_sel_hi:[1,0]
	v_pk_mul_f32 v[32:33], v[32:33], v[106:107] op_sel_hi:[1,0]
	v_pk_mul_f32 v[34:35], v[34:35], v[106:107] op_sel_hi:[1,0]
	v_pk_mul_f32 v[36:37], v[36:37], v[106:107] op_sel_hi:[1,0]
	v_pk_mul_f32 v[38:39], v[38:39], v[106:107] op_sel_hi:[1,0]
	v_pk_mul_f32 v[52:53], v[52:53], v[106:107] op_sel_hi:[1,0]
	v_pk_mul_f32 v[54:55], v[54:55], v[106:107] op_sel_hi:[1,0]
	v_pk_mul_f32 v[48:49], v[48:49], v[106:107] op_sel_hi:[1,0]
	v_pk_mul_f32 v[50:51], v[50:51], v[106:107] op_sel_hi:[1,0]
	v_pk_mul_f32 v[60:61], v[60:61], v[106:107] op_sel_hi:[1,0]
	v_pk_mul_f32 v[62:63], v[62:63], v[106:107] op_sel_hi:[1,0]
	v_pk_mul_f32 v[56:57], v[56:57], v[106:107] op_sel_hi:[1,0]
	v_pk_mul_f32 v[58:59], v[58:59], v[106:107] op_sel_hi:[1,0]
	v_pk_fma_f32 v[46:47], v[64:65], v[46:47], v[2:3]
	v_pk_fma_f32 v[44:45], v[66:67], v[44:45], v[0:1]
	v_pk_fma_f32 v[42:43], v[72:73], v[42:43], v[6:7]
	v_pk_fma_f32 v[40:41], v[74:75], v[40:41], v[4:5]
	v_pk_fma_f32 v[106:107], v[70:71], v[34:35], v[10:11]
	v_pk_fma_f32 v[108:109], v[80:81], v[32:33], v[8:9]
	v_cvt_pk_bf16_f32 v32, v44, v45
	v_cvt_pk_bf16_f32 v33, v46, v47
	v_cvt_pk_bf16_f32 v34, v40, v41
	v_cvt_pk_bf16_f32 v35, v42, v43
	v_pk_fma_f32 v[38:39], v[76:77], v[38:39], v[14:15]
	v_pk_fma_f32 v[36:37], v[78:79], v[36:37], v[12:13]
	global_store_dwordx4 v[68:69], v[32:35], off
	v_pk_fma_f32 v[54:55], v[82:83], v[54:55], v[22:23]
	v_pk_fma_f32 v[52:53], v[84:85], v[52:53], v[20:21]
	v_cvt_pk_bf16_f32 v32, v36, v37
	v_cvt_pk_bf16_f32 v33, v38, v39
	v_cvt_pk_bf16_f32 v34, v108, v109
	v_cvt_pk_bf16_f32 v35, v106, v107
	v_pk_fma_f32 v[50:51], v[86:87], v[50:51], v[18:19]
	v_pk_fma_f32 v[48:49], v[88:89], v[48:49], v[16:17]
	global_store_dwordx4 v[68:69], v[32:35], off offset:1024
	v_pk_fma_f32 v[62:63], v[90:91], v[62:63], v[30:31]
	v_pk_fma_f32 v[60:61], v[92:93], v[60:61], v[28:29]
	v_cvt_pk_bf16_f32 v32, v52, v53
	v_cvt_pk_bf16_f32 v33, v54, v55
	v_cvt_pk_bf16_f32 v34, v48, v49
	v_cvt_pk_bf16_f32 v35, v50, v51
	v_pk_fma_f32 v[58:59], v[94:95], v[58:59], v[26:27]
	v_pk_fma_f32 v[56:57], v[96:97], v[56:57], v[24:25]
	global_store_dwordx4 v[68:69], v[32:35], off offset:2048
	s_nop 1
	v_cvt_pk_bf16_f32 v32, v60, v61
	v_cvt_pk_bf16_f32 v33, v62, v63
	v_cvt_pk_bf16_f32 v34, v56, v57
	v_cvt_pk_bf16_f32 v35, v58, v59
	global_store_dwordx4 v[68:69], v[32:35], off offset:3072
	v_lshl_add_u64 v[68:69], v[68:69], 0, s[0:1]
	s_cbranch_scc0 .LBB0_105

; #define LAS __attribute__((address_space(3)))
; __device__ __forceinline__ void attn_unit(LAS unsigned char* lds, const bf16* UA, bf16* Y, int bl, int h, int qb,
;                                           const float* qkg, const float* rel_bias, const float* lamv, const float* dgain, float lam_init, int tid, int wave, int lane) {
;     const int x = lane & 15, g = lane >> 4, m = wave >> 2, wq = wave & 3;
;     float gqm = fabsf(qkg[lane]), gkm = fabsf(qkg[64 + lane]), bm = lane < 32 ? fabsf(rel_bias[lane * 8 + h]) : 0.f;
;     gqm = wave_max(gqm); gkm = wave_max(gkm); bm = wave_max(bm);
;     const float Mb = (8.0f * gqm * gkm * 1.02f + bm) * LOG2E + 1.0f;
;     const float s01 = wave_sum(lamv[lane] * lamv[64 + lane]), s23 = wave_sum(lamv[128 + lane] * lamv[192 + lane]);
;     const float lam = __expf(s01) - __expf(s23) + lam_init;
;     const float cb_far = rel_bias[15 * 8 + h] * LOG2E - Mb;
;     LAS float* tbl = (LAS float*)(lds + AT_TBL);
;     if (tid < 255) { const int rel = tid - 191, n = rel < 0 ? -rel : rel;
;         int bk = n < 8 ? n : (8 + (31 - __clz(n * n)) - 6); if (bk > 15) bk = 15; if (rel > 0) bk += 16;
;         tbl[tid] = (rel_bias[bk * 8 + h] - rel_bias[15 * 8 + h]) * LOG2E; }
.LBB0_517:
	s_and_b64 vcc, exec, s[0:1]
	s_cbranch_vccz .LBB0_528
	v_readlane_b32 s0, v255, 14
	v_lshlrev_b32_e32 v6, 2, v187
	v_readlane_b32 s1, v255, 15
	s_nop 4
	global_load_dword v0, v6, s[0:1]
	global_load_dword v2, v6, s[0:1] offset:256
	s_and_b32 s11, s56, 7
	v_readlane_b32 s100, v255, 20
	v_readlane_b32 s101, v255, 21
	v_readlane_b32 s20, v252, 43
	v_readlane_b32 s21, v252, 44
	v_add_u32_e32 v235, 0xffffff41, v186
	v_sub_u32_e32 v236, 0xbf, v186
	v_cmp_gt_i32_e32 vcc, 0xbf, v186
	s_lshl_b32 s7, s11, 2
	v_mov_b32_e32 v234, s7
	v_cndmask_b32_e32 v235, v235, v236, vcc
	global_load_dword v240, v6, s[100:101]
	global_load_dword v241, v6, s[100:101] offset:256
	global_load_dword v232, v6, s[100:101] offset:512
	global_load_dword v233, v6, s[100:101] offset:768
	global_load_dword v239, v234, s[20:21] offset:480
	v_mul_lo_u32 v236, v235, v235
	v_ffbh_u32_e32 v236, v236
	v_sub_u32_e32 v236, 33, v236
	v_min_u32_e32 v236, 15, v236
	v_cmp_gt_i32_e32 vcc, 8, v235
	s_nop 1
	v_cndmask_b32_e32 v235, v236, v235, vcc
	v_lshlrev_b32_e32 v235, 3, v235
	v_add_u32_e32 v236, 0x80, v235
	v_cmp_lt_i32_e32 vcc, 0xbf, v186
	s_nop 1
	v_cndmask_b32_e32 v235, v235, v236, vcc
	v_or_b32_e32 v236, s11, v235
	v_ashrrev_i32_e32 v237, 31, v236
	v_lshl_add_u64 v[236:237], v[236:237], 2, s[20:21]
	global_load_dword v238, v[236:237], off
	v_cmp_gt_u32_e32 vcc, 32, v187
	v_mov_b32_e32 v4, 0
	s_and_saveexec_b64 s[0:1], vcc
	s_cbranch_execz .LBB0_520
	s_lshl_b32 s7, s11, 2
	v_readlane_b32 s12, v252, 35
	v_lshl_or_b32 v1, v187, 5, s7
	v_readlane_b32 s20, v252, 43
	v_readlane_b32 s21, v252, 44
	v_readlane_b32 s13, v252, 36
	v_readlane_b32 s14, v252, 37
	v_readlane_b32 s15, v252, 38
	v_readlane_b32 s16, v252, 39
	v_readlane_b32 s17, v252, 40
	global_load_dword v1, v1, s[20:21]
	v_readlane_b32 s18, v252, 41
	v_readlane_b32 s19, v252, 42
	v_readlane_b32 s22, v252, 45
	v_readlane_b32 s23, v252, 46
	v_readlane_b32 s24, v252, 47
	v_readlane_b32 s25, v252, 48
	v_readlane_b32 s26, v252, 49
	v_readlane_b32 s27, v252, 50
	s_waitcnt vmcnt(0)
	v_and_b32_e32 v4, 0x7fffffff, v1
; #define LAS __attribute__((address_space(3)))
; __device__ __forceinline__ void attn_unit(LAS unsigned char* lds, const bf16* UA, bf16* Y, int bl, int h, int qb,
;                                           const float* qkg, const float* rel_bias, const float* lamv, const float* dgain, float lam_init, int tid, int wave, int lane) {
;     ...
;     float gqm = fabsf(qkg[lane]), gkm = fabsf(qkg[64 + lane]), bm = lane < 32 ? fabsf(rel_bias[lane * 8 + h]) : 0.f;
;     gqm = wave_max(gqm); gkm = wave_max(gkm); bm = wave_max(bm);
;     const float Mb = (8.0f * gqm * gkm * 1.02f + bm) * LOG2E + 1.0f;
;     const float s01 = wave_sum(lamv[lane] * lamv[64 + lane]), s23 = wave_sum(lamv[128 + lane] * lamv[192 + lane]);
;     const float lam = __expf(s01) - __expf(s23) + lam_init;
;     const float cb_far = rel_bias[15 * 8 + h] * LOG2E - Mb;
;     LAS float* tbl = (LAS float*)(lds + AT_TBL);
;     if (tid < 255) { const int rel = tid - 191, n = rel < 0 ? -rel : rel;
;         int bk = n < 8 ? n : (8 + (31 - __clz(n * n)) - 6); if (bk > 15) bk = 15; if (rel > 0) bk += 16;
;         tbl[tid] = (rel_bias[bk * 8 + h] - rel_bias[15 * 8 + h]) * LOG2E; }
.LBB0_520:
	s_or_b64 exec, exec, s[0:1]
	v_readlane_b32 s0, v255, 20
	v_readlane_b32 s1, v255, 21
	s_nop 4
	v_mov_b32_e32 v11, v240
	v_mov_b32_e32 v12, v241
	v_cmp_lt_i32_e32 vcc, v222, v216
	s_waitcnt vmcnt(3)
	v_and_b32_e32 v1, 0x7fffffff, v0
	v_max_f32_e64 v0, |v0|, |v0|
	v_cndmask_b32_e32 v5, v215, v222, vcc
	v_lshlrev_b32_e32 v7, 2, v5
	ds_bpermute_b32 v1, v7, v1
	v_cmp_lt_i32_e32 vcc, v221, v216
	s_waitcnt vmcnt(2)
	v_and_b32_e32 v3, 0x7fffffff, v2
	ds_bpermute_b32 v3, v7, v3
	ds_bpermute_b32 v5, v7, v4
	s_waitcnt lgkmcnt(2)
	v_max_f32_e32 v1, v1, v1
	v_max_f32_e32 v0, v0, v1
	v_cndmask_b32_e32 v1, v215, v221, vcc
	v_lshlrev_b32_e32 v8, 2, v1
	ds_bpermute_b32 v1, v8, v0
	v_cmp_lt_i32_e32 vcc, v220, v216
	v_readlane_b32 s12, v252, 35
	v_readlane_b32 s20, v252, 43
	v_readlane_b32 s21, v252, 44
	s_waitcnt lgkmcnt(0)
	v_max_f32_e32 v1, v1, v1
	v_max_f32_e32 v0, v0, v1
	v_cndmask_b32_e32 v1, v215, v220, vcc
	v_lshlrev_b32_e32 v9, 2, v1
	ds_bpermute_b32 v1, v9, v0
	v_cmp_lt_i32_e32 vcc, v219, v216
	v_max_f32_e32 v3, v3, v3
	v_max_f32_e64 v2, |v2|, |v2|
	v_max_f32_e32 v5, v5, v5
	s_waitcnt lgkmcnt(0)
	v_max_f32_e32 v1, v1, v1
	v_max_f32_e32 v0, v0, v1
	v_cndmask_b32_e32 v1, v215, v219, vcc
	v_lshlrev_b32_e32 v10, 2, v1
	ds_bpermute_b32 v1, v10, v0
	v_cmp_lt_i32_e32 vcc, v218, v216
	v_max_f32_e32 v4, v4, v4
	v_max_f32_e32 v2, v2, v3
	v_max_f32_e32 v4, v4, v5
	s_waitcnt lgkmcnt(0)
	v_max_f32_e32 v1, v1, v1
	v_max_f32_e32 v0, v0, v1
	v_cndmask_b32_e32 v1, v215, v218, vcc
	v_lshlrev_b32_e32 v138, 2, v1
	ds_bpermute_b32 v3, v8, v2
	ds_bpermute_b32 v5, v8, v4
	ds_bpermute_b32 v1, v138, v0
	v_cmp_lt_i32_e32 vcc, v217, v216
	v_readlane_b32 s13, v252, 36
	s_waitcnt lgkmcnt(2)
	v_max_f32_e32 v3, v3, v3
	s_waitcnt lgkmcnt(1)
	v_max_f32_e32 v5, v5, v5
	v_max_f32_e32 v2, v2, v3
	v_max_f32_e32 v4, v4, v5
	ds_bpermute_b32 v3, v9, v2
	ds_bpermute_b32 v5, v9, v4
	s_waitcnt lgkmcnt(2)
	v_max_f32_e32 v1, v1, v1
	v_max_f32_e32 v0, v0, v1
	v_cndmask_b32_e32 v1, v215, v217, vcc
	s_waitcnt lgkmcnt(1)
	v_max_f32_e32 v3, v3, v3
	s_waitcnt lgkmcnt(0)
	v_max_f32_e32 v5, v5, v5
	v_max_f32_e32 v2, v2, v3
	v_max_f32_e32 v4, v4, v5
	ds_bpermute_b32 v3, v10, v2
	ds_bpermute_b32 v5, v10, v4
	v_lshlrev_b32_e32 v139, 2, v1
	ds_bpermute_b32 v1, v139, v0
	v_readlane_b32 s14, v252, 37
	s_waitcnt lgkmcnt(2)
	v_max_f32_e32 v3, v3, v3
	s_waitcnt lgkmcnt(1)
	v_max_f32_e32 v5, v5, v5
	v_max_f32_e32 v2, v2, v3
	v_max_f32_e32 v4, v4, v5
	ds_bpermute_b32 v3, v138, v2
	ds_bpermute_b32 v5, v138, v4
	v_readlane_b32 s15, v252, 38
	v_readlane_b32 s16, v252, 39
	v_readlane_b32 s17, v252, 40
	s_waitcnt lgkmcnt(1)
	v_max_f32_e32 v3, v3, v3
	s_waitcnt lgkmcnt(0)
	v_max_f32_e32 v5, v5, v5
	v_max_f32_e32 v2, v2, v3
	v_max_f32_e32 v4, v4, v5
	ds_bpermute_b32 v3, v139, v2
	ds_bpermute_b32 v5, v139, v4
	s_waitcnt vmcnt(0)
	v_mul_f32_e32 v13, v11, v12
	ds_bpermute_b32 v13, v7, v13
	v_readlane_b32 s18, v252, 41
	v_readlane_b32 s19, v252, 42
	v_readlane_b32 s22, v252, 45
	v_readlane_b32 s23, v252, 46
	s_waitcnt lgkmcnt(0)
	v_fmac_f32_e32 v13, v11, v12
	ds_bpermute_b32 v11, v8, v13
	v_readlane_b32 s24, v252, 47
	v_readlane_b32 s25, v252, 48
	v_readlane_b32 s26, v252, 49
	v_readlane_b32 s27, v252, 50
	s_waitcnt lgkmcnt(0)
	v_add_f32_e32 v11, v13, v11
	ds_bpermute_b32 v12, v9, v11
	s_waitcnt lgkmcnt(0)
	v_add_f32_e32 v11, v11, v12
	ds_bpermute_b32 v12, v10, v11
	s_waitcnt lgkmcnt(0)
	v_add_f32_e32 v11, v11, v12
	ds_bpermute_b32 v12, v138, v11
	s_waitcnt lgkmcnt(0)
	v_add_f32_e32 v140, v11, v12
	v_mov_b32_e32 v11, v232
	s_nop 0
	v_mov_b32_e32 v6, v233
	s_lshl_b32 s0, s11, 2
	ds_bpermute_b32 v141, v139, v140
	s_waitcnt vmcnt(0)
	v_mul_f32_e32 v12, v11, v6
	ds_bpermute_b32 v7, v7, v12
	s_waitcnt lgkmcnt(0)
	v_fmac_f32_e32 v7, v11, v6
	ds_bpermute_b32 v6, v8, v7
	s_waitcnt lgkmcnt(0)
	v_add_f32_e32 v6, v7, v6
	ds_bpermute_b32 v7, v9, v6
	s_waitcnt lgkmcnt(0)
	v_add_f32_e32 v6, v6, v7
	ds_bpermute_b32 v7, v10, v6
	s_waitcnt lgkmcnt(0)
	v_add_f32_e32 v6, v6, v7
	ds_bpermute_b32 v7, v138, v6
	s_waitcnt lgkmcnt(0)
	v_add_f32_e32 v142, v6, v7
	v_mov_b32_e32 v6, s0
	v_mov_b32_e32 v6, v239
	ds_bpermute_b32 v143, v139, v142
	s_movk_i32 s0, 0xff
	v_cmp_gt_i32_e32 vcc, s0, v186
	s_and_saveexec_b64 s[0:1], vcc
	s_cbranch_execz .LBB0_522
	s_movk_i32 s7, 0xbf
	v_add_u32_e32 v7, 0xffffff41, v186
	v_sub_u32_e32 v8, 0xbf, v186
	v_cmp_gt_i32_e32 vcc, s7, v186
	v_readlane_b32 s12, v252, 35
	v_readlane_b32 s20, v252, 43
	v_cndmask_b32_e32 v7, v7, v8, vcc
	v_mul_lo_u32 v8, v7, v7
	v_ffbh_u32_e32 v8, v8
	v_sub_u32_e32 v8, 33, v8
	v_min_u32_e32 v8, 15, v8
	v_cmp_gt_i32_e32 vcc, 8, v7
	v_readlane_b32 s21, v252, 44
	v_readlane_b32 s13, v252, 36
	v_cndmask_b32_e32 v7, v8, v7, vcc
	v_lshlrev_b32_e32 v7, 3, v7
	v_add_u32_e32 v8, 0x80, v7
	v_cmp_lt_i32_e32 vcc, s7, v186
	v_readlane_b32 s14, v252, 37
	v_readlane_b32 s15, v252, 38
	v_cndmask_b32_e32 v7, v7, v8, vcc
	v_or_b32_e32 v8, s11, v7
	v_ashrrev_i32_e32 v9, 31, v8
	v_lshl_add_u64 v[8:9], v[8:9], 2, s[20:21]
	v_mov_b32_e32 v7, v238
	v_lshl_add_u32 v8, v186, 2, 0
	v_add_u32_e32 v8, 0x12000, v8
	v_readlane_b32 s16, v252, 39
	v_readlane_b32 s17, v252, 40
	v_readlane_b32 s18, v252, 41
	v_readlane_b32 s19, v252, 42
	v_readlane_b32 s22, v252, 45
	v_readlane_b32 s23, v252, 46
	v_readlane_b32 s24, v252, 47
	v_readlane_b32 s25, v252, 48
	v_readlane_b32 s26, v252, 49
	v_readlane_b32 s27, v252, 50
	s_waitcnt vmcnt(0)
	v_sub_f32_e32 v7, v7, v6
	v_mul_f32_e32 v7, 0x3fb8aa3b, v7
	ds_write_b32 v8, v7

; #define LAS __attribute__((address_space(3)))
; #define AT_LOAD(kt) do { _Pragma("unroll") for (int j = 0; j < 2; ++j) { const int c = tid + 512 * j; \
;         rk[j] = *(const u32x4*)(ksrc + (size_t)((kt) * 64 + (c >> 4)) * 3072 + (c & 15) * 8); \
;         rv[j] = *(const u32x4*)(vsrc + (size_t)((kt) * 64 + (c >> 4)) * 3072 + (c & 15) * 8); } } while (0)
; __device__ __forceinline__ void attn_unit(LAS unsigned char* lds, const bf16* UA, bf16* Y, int bl, int h, int qb,
;                                           const float* qkg, const float* rel_bias, const float* lamv, const float* dgain, float lam_init, int tid, int wave, int lane) {
;     ...
;     for (int kt = 0; kt < NT; ++kt) {
;         const int buf = kt & 1;
;         if (kt + 1 < NT) AT_LOAD(kt + 1);
;         if (kt <= qc) {
;             const bool far_ = (qc - kt) >= 3;
;             const LAS unsigned char* Kb = lds + AT_K + buf * AT_KBUF;
;             const LAS unsigned char* Vb = lds + AT_V + buf * AT_VBUF;
;             f32x4 S[4][2];
;             bf16x8 kf[4][2];
; #pragma unroll
;             for (int kb = 0; kb < 4; ++kb)
; #pragma unroll
;                 for (int ks = 0; ks < 2; ++ks) kf[kb][ks] = *(const LAS bf16x8*)(Kb + koff + (16 * kb) * AT_KROW + ks * 64);
;             __builtin_amdgcn_s_setprio(1);
; #pragma unroll
;             for (int kb = 0; kb < 4; ++kb)
; #pragma unroll
;                 for (int qb2 = 0; qb2 < 2; ++qb2) S[kb][qb2] = __builtin_amdgcn_mfma_f32_16x16x32_bf16(kf[kb][0], qr[qb2][0], CI, 0, 0, 0);
; #pragma unroll
;             for (int kb = 0; kb < 4; ++kb)
; #pragma unroll
;                 for (int qb2 = 0; qb2 < 2; ++qb2) S[kb][qb2] = __builtin_amdgcn_mfma_f32_16x16x32_bf16(kf[kb][1], qr[qb2][1], S[kb][qb2], 0, 0, 0);
;             __builtin_amdgcn_s_setprio(0);
;             if (!far_) {
;                 const int rbase = 64 * kt - (q0 + x) + 191 + 4 * g;
; #pragma unroll
;                 for (int kb = 0; kb < 4; ++kb)
; #pragma unroll
;                     for (int qb2 = 0; qb2 < 2; ++qb2)
; #pragma unroll
;                         for (int i = 0; i < 4; ++i) S[kb][qb2][i] += tbl[rbase + 16 * kb - 16 * qb2 + i];
.LBB0_525:
	s_and_b32 s43, s11, 1
	s_mul_i32 s44, s43, 0x4800
	v_add_u32_e32 v124, s44, v150
	ds_read_b128 v[100:103], v124
	ds_read_b128 v[104:107], v124 offset:64
	ds_read_b128 v[108:111], v124 offset:4608
	ds_read_b128 v[112:115], v124 offset:4672
	ds_read_b128 v[116:119], v124 offset:9216
	ds_read_b128 v[152:155], v124 offset:9280
	ds_read_b128 v[120:123], v124 offset:13824
	ds_read_b128 v[156:159], v124 offset:13888
	v_lshl_add_u64 v[84:85], v[134:135], 0, s[12:13]
	s_mov_b32 s24, 0x23860000
	v_add_co_u32_e32 v86, vcc, s24, v84
	v_lshl_add_u64 v[92:93], v[136:137], 0, s[12:13]
	s_nop 0
	v_addc_co_u32_e32 v87, vcc, 0, v85, vcc
	v_add_co_u32_e32 v88, vcc, 0x23861000, v84
	s_nop 0
	v_addc_co_u32_e32 v89, vcc, 0, v85, vcc
	v_add_co_u32_e32 v94, vcc, 0x23860000, v92
	global_load_dwordx4 v[84:87], v[86:87], off offset:2048
	s_nop 0
	global_load_dwordx4 v[88:91], v[88:89], off
	v_addc_co_u32_e32 v95, vcc, 0, v93, vcc
	v_add_co_u32_e32 v96, vcc, 0x23861000, v92
	s_cmp_gt_u32 s11, s27
	s_nop 0
	v_addc_co_u32_e32 v97, vcc, 0, v93, vcc
	global_load_dwordx4 v[92:95], v[94:95], off offset:2048
	s_nop 0
	global_load_dwordx4 v[96:99], v[96:97], off
	s_cbranch_scc1 .Latt_skipw
	s_setprio 1
	s_waitcnt lgkmcnt(7)
	v_mfma_f32_16x16x32_bf16 v[124:127], v[100:103], v[72:75], v[64:67]
	s_cmp_gt_u32 s42, 2
	v_mfma_f32_16x16x32_bf16 v[100:103], v[100:103], v[80:83], v[64:67]
	s_waitcnt lgkmcnt(5)
	v_mfma_f32_16x16x32_bf16 v[160:163], v[108:111], v[72:75], v[64:67]
	v_mfma_f32_16x16x32_bf16 v[108:111], v[108:111], v[80:83], v[64:67]
	s_waitcnt lgkmcnt(3)
	v_mfma_f32_16x16x32_bf16 v[164:167], v[116:119], v[72:75], v[64:67]
	v_mfma_f32_16x16x32_bf16 v[188:191], v[116:119], v[80:83], v[64:67]
	s_waitcnt lgkmcnt(1)
	v_mfma_f32_16x16x32_bf16 v[192:195], v[120:123], v[72:75], v[64:67]
	v_mfma_f32_16x16x32_bf16 v[196:199], v[120:123], v[80:83], v[64:67]
	v_mfma_f32_16x16x32_bf16 v[128:131], v[104:107], v[68:71], v[124:127]
	v_mfma_f32_16x16x32_bf16 v[124:127], v[104:107], v[76:79], v[100:103]
	v_mfma_f32_16x16x32_bf16 v[120:123], v[112:115], v[68:71], v[160:163]
	v_mfma_f32_16x16x32_bf16 v[116:119], v[112:115], v[76:79], v[108:111]
	v_mfma_f32_16x16x32_bf16 v[112:115], v[152:155], v[68:71], v[164:167]
	v_mfma_f32_16x16x32_bf16 v[108:111], v[152:155], v[76:79], v[188:191]
	s_waitcnt lgkmcnt(0)
	v_mfma_f32_16x16x32_bf16 v[104:107], v[156:159], v[68:71], v[192:195]
	v_mfma_f32_16x16x32_bf16 v[100:103], v[156:159], v[76:79], v[196:199]
	s_setprio 0
	s_cbranch_scc1 .LBB0_523
	v_add_u32_e32 v156, s37, v151
	v_add_u32_e32 v152, 0x123bc, v156
	v_add_u32_e32 v154, 0x123c4, v156
	ds_read2_b32 v[152:153], v152 offset1:1
	ds_read2_b32 v[154:155], v154 offset1:1
	v_add_u32_e32 v157, 0x123fc, v156
	v_add_u32_e32 v158, 0x12404, v156
	v_add_u32_e32 v159, 0x1243c, v156
	s_waitcnt lgkmcnt(1)
	v_pk_add_f32 v[124:125], v[124:125], v[152:153]
	s_waitcnt lgkmcnt(0)
	v_pk_add_f32 v[126:127], v[126:127], v[154:155]
	ds_read2_b32 v[152:153], v157 offset1:1
	ds_read2_b32 v[154:155], v158 offset1:1
	v_add_u32_e32 v160, 0x12444, v156
	v_add_u32_e32 v157, 0x1247c, v156
	v_add_u32_e32 v158, 0x12484, v156
	s_waitcnt lgkmcnt(1)
	v_pk_add_f32 v[128:129], v[128:129], v[152:153]
	s_waitcnt lgkmcnt(0)
	v_pk_add_f32 v[130:131], v[130:131], v[154:155]
	v_pk_add_f32 v[118:119], v[118:119], v[154:155]
	v_pk_add_f32 v[116:117], v[116:117], v[152:153]
	ds_read2_b32 v[152:153], v159 offset1:1
	ds_read2_b32 v[154:155], v160 offset1:1
	s_waitcnt lgkmcnt(1)
	v_pk_add_f32 v[120:121], v[120:121], v[152:153]
	s_waitcnt lgkmcnt(0)
	v_pk_add_f32 v[122:123], v[122:123], v[154:155]
	v_pk_add_f32 v[110:111], v[110:111], v[154:155]
	v_pk_add_f32 v[108:109], v[108:109], v[152:153]
	v_add_u32_e32 v152, 0x124bc, v156
	v_add_u32_e32 v154, 0x124c4, v156
	ds_read2_b32 v[152:153], v152 offset1:1
	ds_read2_b32 v[154:155], v154 offset1:1
	s_waitcnt lgkmcnt(1)
	v_pk_add_f32 v[104:105], v[104:105], v[152:153]
	s_waitcnt lgkmcnt(0)
	v_pk_add_f32 v[106:107], v[106:107], v[154:155]
	ds_read2_b32 v[152:153], v157 offset1:1
	ds_read2_b32 v[154:155], v158 offset1:1
	s_waitcnt lgkmcnt(1)
	v_pk_add_f32 v[112:113], v[112:113], v[152:153]
	s_waitcnt lgkmcnt(0)
	v_pk_add_f32 v[114:115], v[114:115], v[154:155]
	v_pk_add_f32 v[102:103], v[102:103], v[154:155]
	v_pk_add_f32 v[100:101], v[100:101], v[152:153]
	s_branch .LBB0_523
.Latt_skipw:
	s_waitcnt lgkmcnt(0)
	s_branch .LBB0_524

; template <int MODE, bool SRC32>
; __device__ __forceinline__ void phase_mod(const float* x32, _Float16* xh, float* out32, bf16* h, const float* gprev, const float* gain, const float* shiftv, const float* scalev, int wave, int lane) {
;     const int blk = (int)blockIdx.x, b = blk >> 5, r0 = blk * 128 + wave * 16;
;     f32x4 A[8], Sh[8], G3[8];
; #pragma unroll
;     for (int k = 0; k < 8; ++k) {
;         const int d = 512 * (k >> 1) + 8 * lane + 4 * (k & 1);
;         if (MODE != 2) { const f32x4 g = *(const f32x4*)(gain + d), sc = *(const f32x4*)(scalev + (size_t)b * NMOD + d); A[k] = g * (sc + 1.0f); Sh[k] = *(const f32x4*)(shiftv + (size_t)b * NMOD + d); }
;         if (MODE != 0) G3[k] = *(const f32x4*)(gprev + d);
;     }
;     for (int i = 0; i < 16; ++i) {
;         const size_t ro = (size_t)(r0 + i) * D + 8 * lane;
;         f32x4 v[8]; float ss = 0.f;
; #pragma unroll
;         for (int j = 0; j < 4; ++j) {
;             if (SRC32) { v[2 * j] = *(const f32x4*)(x32 + ro + 512 * j); v[2 * j + 1] = *(const f32x4*)(x32 + ro + 512 * j + 4); }
;             else h8_to_f(*(const h16x8*)(xh + ro + 512 * j), v[2 * j], v[2 * j + 1]);
;         }
.LBB0_1130:
	s_cmp_lt_i32 s44, 30
	s_cselect_b64 s[0:1], -1, 0
	s_cmp_gt_i32 s45, 29
	s_cselect_b64 s[2:3], -1, 0
	s_and_b64 s[0:1], s[0:1], s[2:3]
	s_and_b64 vcc, exec, s[0:1]
	s_cbranch_vccz .LBB0_1133
	v_readlane_b32 s8, v252, 19
	v_lshlrev_b32_e32 v32, 5, v68
	v_mov_b32_e32 v33, 0
	v_readlane_b32 s16, v252, 27
	v_readlane_b32 s17, v252, 28
	s_mov_b64 s[0:1], 0xe000
	v_readlane_b32 s4, v252, 63
	v_lshl_add_u64 v[24:25], s[16:17], 0, v[32:33]
	s_waitcnt vmcnt(0)
	v_add_co_u32_e32 v18, vcc, 0xe000, v24
	v_lshl_add_u64 v[16:17], v[24:25], 0, s[0:1]
	s_nop 0
	v_addc_co_u32_e32 v19, vcc, 0, v25, vcc
	global_load_dwordx4 v[0:3], v[18:19], off
	global_load_dwordx4 v[4:7], v[16:17], off offset:2064
	global_load_dwordx4 v[8:11], v[16:17], off offset:16
	global_load_dwordx4 v[12:15], v[16:17], off offset:2048
	s_mov_b64 s[0:1], 0xf000
	v_add_co_u32_e32 v34, vcc, 0xf000, v24
	v_lshl_add_u64 v[26:27], v[24:25], 0, s[0:1]
	s_nop 0
	v_addc_co_u32_e32 v35, vcc, 0, v25, vcc
	s_mov_b64 s[0:1], 0xf800
	global_load_dwordx4 v[16:19], v[34:35], off
	global_load_dwordx4 v[20:23], v[26:27], off offset:16
	v_lshl_add_u64 v[36:37], v[24:25], 0, s[0:1]
	global_load_dwordx4 v[24:27], v[34:35], off offset:2048
	global_load_dwordx4 v[28:31], v[36:37], off offset:16
	s_lshl_b32 s0, s6, 4
	v_readlane_b32 s1, v253, 7
	v_cmp_lt_i32_e32 vcc, v222, v216
	s_add_i32 s0, s0, s1
	s_ashr_i32 s1, s0, 31
	v_cndmask_b32_e32 v34, v215, v222, vcc
	v_cmp_lt_i32_e32 vcc, v221, v216
	v_lshlrev_b32_e32 v52, 2, v34
	s_lshl_b64 s[2:3], s[0:1], 12
	v_cndmask_b32_e32 v34, v215, v221, vcc
	v_cmp_lt_i32_e32 vcc, v220, v216
	v_lshlrev_b32_e32 v53, 2, v34
	v_readlane_b32 s5, v253, 0
	v_cndmask_b32_e32 v34, v215, v220, vcc
	v_cmp_lt_i32_e32 vcc, v219, v216
	v_lshlrev_b32_e32 v54, 2, v34
	s_add_u32 s2, s4, s2
	v_cndmask_b32_e32 v34, v215, v219, vcc
	v_cmp_lt_i32_e32 vcc, v218, v216
	v_lshlrev_b32_e32 v55, 2, v34
	s_addc_u32 s3, s5, s3
	v_cndmask_b32_e32 v34, v215, v218, vcc
	v_cmp_lt_i32_e32 vcc, v217, v216
	s_lshl_b64 s[0:1], s[0:1], 13
	v_lshlrev_b32_e32 v56, 2, v34
	v_cndmask_b32_e32 v34, v215, v217, vcc
	s_add_u32 s0, s40, s0
	v_lshlrev_b32_e32 v57, 2, v34
	v_lshlrev_b32_e32 v34, 4, v68
	v_mov_b32_e32 v35, v33
	s_addc_u32 s1, s41, s1
	v_lshl_add_u64 v[48:49], s[2:3], 0, v[34:35]
	v_lshl_add_u64 v[50:51], s[0:1], 0, v[32:33]
	s_mov_b64 s[2:3], 0
	v_mov_b32_e32 v58, 0x358637bd
	s_mov_b32 s6, 0xf800000
	v_mov_b32_e32 v59, 0x260
	s_movk_i32 s7, 0x1000
	s_mov_b64 s[4:5], 0x1000
	v_readlane_b32 s9, v252, 20
	v_readlane_b32 s10, v252, 21
	v_readlane_b32 s11, v252, 22
	v_readlane_b32 s12, v252, 23
	v_readlane_b32 s13, v252, 24
	v_readlane_b32 s14, v252, 25
	v_readlane_b32 s15, v252, 26
	v_readlane_b32 s18, v252, 29
	v_readlane_b32 s19, v252, 30
	v_readlane_b32 s20, v252, 31
	v_readlane_b32 s21, v252, 32
	v_readlane_b32 s22, v252, 33
	v_readlane_b32 s23, v252, 34
	global_load_dwordx4 v[112:115], v[48:49], off
	global_load_dwordx4 v[116:119], v[48:49], off offset:1024
	global_load_dwordx4 v[120:123], v[48:49], off offset:2048
	global_load_dwordx4 v[124:127], v[48:49], off offset:3072
	v_lshl_add_u64 v[48:49], v[48:49], 0, s[4:5]
	s_waitcnt vmcnt(0)
.LBB0_1132:
	s_waitcnt vmcnt(8)
	v_mov_b64_e32 v[32:33], v[112:113]
	v_mov_b64_e32 v[34:35], v[114:115]
	v_mov_b64_e32 v[36:37], v[116:117]
	v_mov_b64_e32 v[38:39], v[118:119]
	v_mov_b64_e32 v[40:41], v[120:121]
	v_mov_b64_e32 v[42:43], v[122:123]
	v_mov_b64_e32 v[44:45], v[124:125]
	v_mov_b64_e32 v[46:47], v[126:127]
	v_lshl_add_u64 v[76:77], v[50:51], 0, s[2:3]
	v_add_co_u32_e32 v78, vcc, s7, v76
	s_add_u32 s2, s2, 0x2000
	s_nop 0
	v_addc_co_u32_e32 v79, vcc, 0, v77, vcc
	s_addc_u32 s3, s3, 0
	s_cmp_lg_u32 s2, 0x20000
	s_cbranch_scc0 .Lmodpf2_skip
	global_load_dwordx4 v[112:115], v[48:49], off
	global_load_dwordx4 v[116:119], v[48:49], off offset:1024
	global_load_dwordx4 v[120:123], v[48:49], off offset:2048
	global_load_dwordx4 v[124:127], v[48:49], off offset:3072
	v_lshl_add_u64 v[48:49], v[48:49], 0, s[4:5]
.Lmodpf2_skip:
	v_cvt_f32_f16_sdwa v61, v32 dst_sel:DWORD dst_unused:UNUSED_PAD src0_sel:WORD_1
	v_cvt_f32_f16_sdwa v63, v33 dst_sel:DWORD dst_unused:UNUSED_PAD src0_sel:WORD_1
	v_cvt_f32_f16_e32 v62, v33
	v_cvt_f32_f16_sdwa v33, v34 dst_sel:DWORD dst_unused:UNUSED_PAD src0_sel:WORD_1
	v_cvt_f32_f16_sdwa v65, v35 dst_sel:DWORD dst_unused:UNUSED_PAD src0_sel:WORD_1
	v_cvt_f32_f16_e32 v60, v32
	v_cvt_f32_f16_e32 v32, v34
	v_cvt_f32_f16_e32 v64, v35
	v_cvt_f32_f16_sdwa v35, v36 dst_sel:DWORD dst_unused:UNUSED_PAD src0_sel:WORD_1
	v_cvt_f32_f16_sdwa v67, v37 dst_sel:DWORD dst_unused:UNUSED_PAD src0_sel:WORD_1
	v_cvt_f32_f16_e32 v34, v36
	v_cvt_f32_f16_e32 v66, v37
	v_cvt_f32_f16_e32 v36, v38
	v_cvt_f32_f16_e32 v68, v39
	v_cvt_f32_f16_sdwa v37, v38 dst_sel:DWORD dst_unused:UNUSED_PAD src0_sel:WORD_1
	v_cvt_f32_f16_sdwa v69, v39 dst_sel:DWORD dst_unused:UNUSED_PAD src0_sel:WORD_1
	v_cvt_f32_f16_sdwa v39, v40 dst_sel:DWORD dst_unused:UNUSED_PAD src0_sel:WORD_1
	v_cvt_f32_f16_e32 v38, v40
	v_cvt_f32_f16_sdwa v71, v41 dst_sel:DWORD dst_unused:UNUSED_PAD src0_sel:WORD_1
	v_cvt_f32_f16_e32 v70, v41
	v_mov_b32_e32 v82, v61
	v_mov_b32_e32 v83, v33
	v_mov_b32_e32 v86, v63
	v_mov_b32_e32 v87, v65
	v_cvt_f32_f16_sdwa v41, v42 dst_sel:DWORD dst_unused:UNUSED_PAD src0_sel:WORD_1
	v_cvt_f32_f16_e32 v40, v42
	v_cvt_f32_f16_sdwa v73, v43 dst_sel:DWORD dst_unused:UNUSED_PAD src0_sel:WORD_1
	v_cvt_f32_f16_e32 v72, v43
	v_cvt_f32_f16_sdwa v43, v44 dst_sel:DWORD dst_unused:UNUSED_PAD src0_sel:WORD_1
	v_cvt_f32_f16_e32 v42, v44
	v_cvt_f32_f16_sdwa v75, v45 dst_sel:DWORD dst_unused:UNUSED_PAD src0_sel:WORD_1
	v_cvt_f32_f16_e32 v74, v45
; __device__ __forceinline__ h16x8 f_to_h8(const f32x4 a, const f32x4 b) { return (h16x8){(_Float16)a[0], (_Float16)a[1], (_Float16)a[2], (_Float16)a[3], (_Float16)b[0], (_Float16)b[1], (_Float16)b[2], (_Float16)b[3]}; }
; template <int MODE, bool SRC32>
; __device__ __forceinline__ void phase_mod(const float* x32, _Float16* xh, float* out32, bf16* h, const float* gprev, const float* gain, const float* shiftv, const float* scalev, int wave, int lane) {
;     ...
; #pragma unroll
;         for (int k = 0; k < 8; ++k) ss += (v[k][0] * v[k][0] + v[k][1] * v[k][1]) + (v[k][2] * v[k][2] + v[k][3] * v[k][3]);
;         ss = wave_sum(ss);
;         float rstd = 1.0f / sqrtf(ss * (1.0f / D) + EPS);
;         if (MODE != 0) {
;             float s2 = 0.f;
; #pragma unroll
;             for (int k = 0; k < 8; ++k) { v[k] = v[k] * rstd * G3[k]; s2 += (v[k][0] * v[k][0] + v[k][1] * v[k][1]) + (v[k][2] * v[k][2] + v[k][3] * v[k][3]); }
; #pragma unroll
;             for (int j = 0; j < 4; ++j) {
;                 if (MODE == 1) *(h16x8*)(xh + ro + 512 * j) = f_to_h8(v[2 * j], v[2 * j + 1]);
;                 else { *(f32x4*)(out32 + ro + 512 * j) = v[2 * j]; *(f32x4*)(out32 + ro + 512 * j + 4) = v[2 * j + 1]; }
;             }
	v_cvt_f32_f16_sdwa v45, v46 dst_sel:DWORD dst_unused:UNUSED_PAD src0_sel:WORD_1
	v_cvt_f32_f16_e32 v44, v46
	v_cvt_f32_f16_sdwa v81, v47 dst_sel:DWORD dst_unused:UNUSED_PAD src0_sel:WORD_1
	v_cvt_f32_f16_e32 v80, v47
	v_mov_b32_e32 v46, v60
	v_mov_b32_e32 v47, v32
	v_mov_b32_e32 v84, v62
	v_mov_b32_e32 v85, v64
	v_mov_b32_e32 v90, v35
	v_mov_b32_e32 v91, v67
	v_pk_mul_f32 v[82:83], v[82:83], v[82:83]
	v_pk_mul_f32 v[86:87], v[86:87], v[86:87]
	v_mov_b32_e32 v88, v34
	v_mov_b32_e32 v89, v66
	v_pk_mul_f32 v[90:91], v[90:91], v[90:91]
	v_pk_fma_f32 v[46:47], v[46:47], v[46:47], v[82:83]
	v_pk_fma_f32 v[82:83], v[84:85], v[84:85], v[86:87]
	v_mul_f32_e32 v92, v36, v36
	v_mul_f32_e32 v94, v68, v68
	v_pk_fma_f32 v[84:85], v[88:89], v[88:89], v[90:91]
	v_pk_add_f32 v[46:47], v[46:47], v[82:83]
	v_pk_mul_f32 v[96:97], v[38:39], v[38:39]
	v_pk_mul_f32 v[98:99], v[70:71], v[70:71]
	v_pk_fma_f32 v[92:93], v[36:37], v[36:37], v[92:93] op_sel_hi:[1,1,0]
	v_pk_fma_f32 v[94:95], v[68:69], v[68:69], v[94:95] op_sel_hi:[1,1,0]
	v_pk_add_f32 v[82:83], v[84:85], v[84:85] op_sel_hi:[0,1]
	v_pk_add_f32 v[46:47], v[46:47], v[46:47] op_sel_hi:[0,1]
	v_mov_b32_e32 v102, v41
	v_mov_b32_e32 v103, v73
	v_mov_b32_e32 v92, v96
	v_mov_b32_e32 v94, v97
	v_mov_b32_e32 v82, v99
	v_mov_b32_e32 v46, v98
	v_mov_b32_e32 v100, v40
	v_mov_b32_e32 v101, v72
	v_pk_mul_f32 v[102:103], v[102:103], v[102:103]
	v_pk_add_f32 v[84:85], v[92:93], v[94:95]
	v_pk_add_f32 v[46:47], v[46:47], v[82:83]
	v_mul_f32_e32 v104, v42, v42
	v_mul_f32_e32 v106, v74, v74
	v_pk_fma_f32 v[86:87], v[100:101], v[100:101], v[102:103]
	v_pk_add_f32 v[46:47], v[84:85], v[46:47]
	v_pk_mul_f32 v[108:109], v[44:45], v[44:45]
	v_pk_mul_f32 v[110:111], v[80:81], v[80:81]
	v_pk_fma_f32 v[104:105], v[42:43], v[42:43], v[104:105] op_sel_hi:[1,1,0]
	v_pk_fma_f32 v[106:107], v[74:75], v[74:75], v[106:107] op_sel_hi:[1,1,0]
	v_pk_add_f32 v[86:87], v[86:87], v[86:87] op_sel_hi:[0,1]
	v_pk_add_f32 v[46:47], v[46:47], v[46:47] op_sel_hi:[0,1]
	v_mov_b32_e32 v104, v108
	v_mov_b32_e32 v106, v109
	v_mov_b32_e32 v86, v110
	v_mov_b32_e32 v46, v111
	v_pk_add_f32 v[88:89], v[104:105], v[106:107]
	v_pk_add_f32 v[46:47], v[86:87], v[46:47]
	s_nop 0
	v_pk_add_f32 v[46:47], v[88:89], v[46:47]
	s_nop 0
	v_add_f32_e32 v46, v46, v47
	ds_bpermute_b32 v47, v52, v46
	s_waitcnt lgkmcnt(0)
	v_add_f32_e32 v46, v46, v47
	ds_bpermute_b32 v47, v53, v46
	s_waitcnt lgkmcnt(0)
	v_add_f32_e32 v46, v46, v47
	ds_bpermute_b32 v47, v54, v46
	s_waitcnt lgkmcnt(0)
	v_add_f32_e32 v46, v46, v47
	ds_bpermute_b32 v47, v55, v46
	s_waitcnt lgkmcnt(0)
	v_add_f32_e32 v46, v46, v47
	ds_bpermute_b32 v47, v56, v46
	s_waitcnt lgkmcnt(0)
	v_add_f32_e32 v46, v46, v47
	ds_bpermute_b32 v47, v57, v46
	s_waitcnt lgkmcnt(0)
	v_add_f32_e32 v46, v46, v47
	v_fmamk_f32 v46, v46, 0x3a000000, v58
	v_mul_f32_e32 v47, 0x4f800000, v46
	v_cmp_gt_f32_e32 vcc, s6, v46
	s_nop 1
	v_cndmask_b32_e32 v46, v46, v47, vcc
	v_sqrt_f32_e32 v47, v46
	s_nop 0
	v_add_u32_e32 v82, -1, v47
	v_add_u32_e32 v83, 1, v47
	v_fma_f32 v84, -v82, v47, v46
	v_fma_f32 v85, -v83, v47, v46
	v_cmp_ge_f32_e64 s[0:1], 0, v84
	s_nop 1
	v_cndmask_b32_e64 v47, v47, v82, s[0:1]
	v_cmp_lt_f32_e64 s[0:1], 0, v85
	s_nop 1
	v_cndmask_b32_e64 v47, v47, v83, s[0:1]
	v_mul_f32_e32 v82, 0x37800000, v47
	v_cndmask_b32_e32 v47, v47, v82, vcc
	v_cmp_class_f32_e32 vcc, v46, v59
	s_nop 1
	v_cndmask_b32_e32 v46, v47, v46, vcc
	v_div_scale_f32 v47, s[0:1], v46, v46, 1.0
	v_rcp_f32_e32 v83, v47
	v_div_scale_f32 v82, vcc, 1.0, v46, 1.0
	v_fma_f32 v84, -v47, v83, 1.0
	v_fmac_f32_e32 v83, v84, v83
	v_mul_f32_e32 v84, v82, v83
	v_fma_f32 v85, -v47, v84, v82
	v_fmac_f32_e32 v84, v85, v83
	v_fma_f32 v47, -v47, v84, v82
	v_div_fmas_f32 v47, v47, v83, v84
	v_div_fixup_f32 v46, v47, v46, 1.0
	v_pk_mul_f32 v[60:61], v[60:61], v[46:47] op_sel_hi:[1,0]
	v_pk_mul_f32 v[62:63], v[62:63], v[46:47] op_sel_hi:[1,0]
	v_pk_mul_f32 v[82:83], v[32:33], v[46:47] op_sel_hi:[1,0]
	v_pk_mul_f32 v[64:65], v[64:65], v[46:47] op_sel_hi:[1,0]
	v_pk_mul_f32 v[84:85], v[34:35], v[46:47] op_sel_hi:[1,0]
	v_pk_mul_f32 v[66:67], v[66:67], v[46:47] op_sel_hi:[1,0]
	v_pk_mul_f32 v[86:87], v[36:37], v[46:47] op_sel_hi:[1,0]
	v_pk_mul_f32 v[68:69], v[68:69], v[46:47] op_sel_hi:[1,0]
	v_pk_mul_f32 v[88:89], v[38:39], v[46:47] op_sel_hi:[1,0]
	v_pk_mul_f32 v[70:71], v[70:71], v[46:47] op_sel_hi:[1,0]
	v_pk_mul_f32 v[90:91], v[40:41], v[46:47] op_sel_hi:[1,0]
	v_pk_mul_f32 v[72:73], v[72:73], v[46:47] op_sel_hi:[1,0]
	v_pk_mul_f32 v[92:93], v[42:43], v[46:47] op_sel_hi:[1,0]
	v_pk_mul_f32 v[74:75], v[74:75], v[46:47] op_sel_hi:[1,0]
	v_pk_mul_f32 v[94:95], v[44:45], v[46:47] op_sel_hi:[1,0]
	v_pk_mul_f32 v[80:81], v[80:81], v[46:47] op_sel_hi:[1,0]
	v_pk_mul_f32 v[34:35], v[2:3], v[62:63]
	v_pk_mul_f32 v[32:33], v[0:1], v[60:61]
	v_pk_mul_f32 v[38:39], v[10:11], v[64:65]
	v_pk_mul_f32 v[36:37], v[8:9], v[82:83]
	v_pk_mul_f32 v[42:43], v[14:15], v[66:67]
	v_pk_mul_f32 v[40:41], v[12:13], v[84:85]
	v_pk_mul_f32 v[46:47], v[6:7], v[68:69]
	v_pk_mul_f32 v[44:45], v[4:5], v[86:87]
	v_pk_mul_f32 v[62:63], v[18:19], v[70:71]
	v_pk_mul_f32 v[60:61], v[16:17], v[88:89]
	v_pk_mul_f32 v[66:67], v[22:23], v[72:73]
	v_pk_mul_f32 v[64:65], v[20:21], v[90:91]
	v_pk_mul_f32 v[70:71], v[26:27], v[74:75]
	v_pk_mul_f32 v[68:69], v[24:25], v[92:93]
	v_pk_mul_f32 v[74:75], v[30:31], v[80:81]
	v_pk_mul_f32 v[72:73], v[28:29], v[94:95]
	global_store_dwordx4 v[76:77], v[32:35], off
	global_store_dwordx4 v[76:77], v[36:39], off offset:16
	global_store_dwordx4 v[76:77], v[40:43], off offset:2048
	global_store_dwordx4 v[76:77], v[44:47], off offset:2064
	global_store_dwordx4 v[78:79], v[60:63], off
	global_store_dwordx4 v[78:79], v[64:67], off offset:16
	global_store_dwordx4 v[78:79], v[68:71], off offset:2048
	global_store_dwordx4 v[78:79], v[72:75], off offset:2064
	s_cbranch_scc1 .LBB0_1132
